# odd in-proj epilogue: row-statistic loads 1-4 and 5-7 issued together (register-limited) with counted waits, instead of eight load/vmcnt(0)/reduce steps
# baseline (speedup 1.0000x reference)
.LBB0_186:
	s_lshl_b32 s6, s18, 8
	s_add_i32 s17, s6, s56
	s_lshl_b32 s6, s19, 8
	v_mov_b32_e32 v146, v1
	v_mov_b32_e32 v147, v169
	s_or_b32 s6, s6, s57
	s_movk_i32 s68, 0x5000
	v_lshl_add_u32 v162, v147, 3, s6
	s_sub_i32 s6, s18, 32
	s_lshr_b32 s6, s6, 2
	s_add_i32 s6, s6, 1
	s_cmp_gt_i32 s18, 31
	s_cselect_b32 s62, s6, 0
	s_lshl_b64 s[6:7], s[62:63], 13
	v_add_u32_e32 v164, s17, v146
	v_lshlrev_b32_e32 v146, 2, v147
	s_add_u32 s6, s53, s6
	v_ashrrev_i32_e32 v147, 31, v146
	v_ashrrev_i32_e32 v165, 31, v164
	s_addc_u32 s7, s54, s7
	v_ashrrev_i32_e32 v163, 31, v162
	v_lshl_add_u64 v[146:147], v[146:147], 2, s[12:13]
	v_lshlrev_b64 v[148:149], 6, v[164:165]
	v_lshl_add_u64 v[134:135], v[162:163], 2, s[6:7]
	v_lshl_add_u64 v[148:149], v[146:147], 0, v[148:149]
	global_load_dwordx4 v[138:141], v[134:135], off offset:16
	global_load_dwordx4 v[142:145], v[134:135], off
	global_load_dwordx4 v[130:133], v[134:135], off offset:528
	s_nop 0
	global_load_dwordx4 v[134:137], v[134:135], off offset:512
	v_add_u32_e32 v166, 16, v164
	global_load_dwordx4 v[172:175], v[148:149], off
	global_load_dwordx4 v[198:201], v[148:149], off offset:1024
	global_load_dwordx4 v[206:209], v[148:149], off offset:2048
	global_load_dwordx4 v[242:245], v[148:149], off offset:3072
	v_ashrrev_i32_e32 v167, 31, v166
	s_mov_b32 s6, 0x358637bd
	s_mov_b32 s18, 0x3a800000
	v_add_u32_e32 v194, 0x80, v164
	v_ashrrev_i32_e32 v195, 31, v194
	v_add_u32_e32 v196, 0x90, v164
	v_ashrrev_i32_e32 v197, 31, v196
	v_add_u32_e32 v202, 0xa0, v164
	v_ashrrev_i32_e32 v203, 31, v202
	v_add_u32_e32 v204, 0xb0, v164
	v_ashrrev_i32_e32 v205, 31, v204
	v_lshlrev_b64 v[162:163], 1, v[162:163]
	s_mov_b32 s70, 0xd000
	s_waitcnt vmcnt(3)
	v_mov_b32_e32 v148, v173
	v_mov_b32_e32 v149, v174
	v_mov_b32_e32 v173, v175
	v_pk_add_f32 v[148:149], v[148:149], v[172:173]
	v_lshlrev_b64 v[172:173], 6, v[166:167]
	v_lshl_add_u64 v[172:173], v[146:147], 0, v[172:173]
	v_pk_add_f32 v[148:149], v[148:149], v[148:149] op_sel:[0,1] op_sel_hi:[1,0]
	s_waitcnt vmcnt(2)
	v_mov_b32_e32 v172, v198
	v_mov_b32_e32 v173, v199
	v_mov_b32_e32 v174, v200
	v_mov_b32_e32 v175, v201
	v_mov_b32_e32 v184, v173
	v_mov_b32_e32 v185, v174
	v_mov_b32_e32 v173, v175
	v_mov_b32_e32 v149, v148
	v_pk_add_f32 v[172:173], v[184:185], v[172:173]
	s_nop 0
	v_permlane16_swap_b32_e32 v148, v149
	v_pk_add_f32 v[172:173], v[172:173], v[172:173] op_sel:[0,1] op_sel_hi:[1,0]
	v_add_f32_e32 v149, v148, v149
	v_mov_b32_e32 v148, v172
	s_nop 1
	v_permlane16_swap_b32_e32 v172, v148
	v_add_f32_e32 v148, v172, v148
	v_mov_b32_e32 v177, v149
	v_mov_b32_e32 v176, v148
	s_nop 0
	v_permlane32_swap_b32_e32 v149, v177
	v_permlane32_swap_b32_e32 v148, v176
	v_pk_add_f32 v[148:149], v[148:149], v[176:177]
	v_mov_b64_e32 v[174:175], s[6:7]
	v_pk_fma_f32 v[148:149], v[148:149], s[18:19], v[174:175] op_sel_hi:[1,0,0]
	v_add_u32_e32 v172, 32, v164
	v_mul_f32_e32 v168, 0x4b800000, v149
	v_cmp_gt_f32_e64 s[6:7], s84, v149
	v_cmp_gt_f32_e32 vcc, s84, v148
	v_ashrrev_i32_e32 v173, 31, v172
	v_cndmask_b32_e64 v149, v149, v168, s[6:7]
	v_rsq_f32_e32 v149, v149
	v_add_u32_e32 v176, 48, v164
	v_ashrrev_i32_e32 v177, 31, v176
	v_lshlrev_b64 v[164:165], 12, v[164:165]
	v_mul_f32_e32 v168, 0x45800000, v149
	v_cndmask_b32_e64 v170, v149, v168, s[6:7]
	v_mul_f32_e32 v149, 0x4b800000, v148
	v_cndmask_b32_e32 v148, v148, v149, vcc
	v_rsq_f32_e32 v148, v148
	v_lshl_add_u64 v[164:165], s[10:11], 0, v[164:165]
	v_pk_fma_f32 v[128:129], v[128:129], v[170:171], v[144:145] op_sel_hi:[1,0,1]
	v_pk_fma_f32 v[126:127], v[126:127], v[170:171], v[142:143] op_sel_hi:[1,0,1]
	v_mul_f32_e32 v149, 0x45800000, v148
	v_cndmask_b32_e32 v168, v148, v149, vcc
	v_lshlrev_b64 v[148:149], 6, v[172:173]
	v_lshl_add_u64 v[148:149], v[146:147], 0, v[148:149]
	v_lshl_add_u64 v[164:165], v[164:165], 0, v[162:163]
	v_pk_fma_f32 v[116:117], v[116:117], v[170:171], v[136:137] op_sel_hi:[1,0,1]
	v_pk_fma_f32 v[114:115], v[114:115], v[170:171], v[134:135] op_sel_hi:[1,0,1]
	v_pk_fma_f32 v[112:113], v[112:113], v[168:169], v[140:141] op_sel_hi:[1,0,1]
	v_pk_fma_f32 v[110:111], v[110:111], v[168:169], v[138:139] op_sel_hi:[1,0,1]
	v_pk_fma_f32 v[100:101], v[100:101], v[168:169], v[136:137] op_sel_hi:[1,0,1]
	v_pk_fma_f32 v[98:99], v[98:99], v[168:169], v[134:135] op_sel_hi:[1,0,1]
	s_waitcnt vmcnt(1)
	v_mov_b32_e32 v184, v206
	v_mov_b32_e32 v185, v207
	v_mov_b32_e32 v186, v208
	v_mov_b32_e32 v187, v209
	v_mov_b32_e32 v148, v185
	v_mov_b32_e32 v149, v186
	v_mov_b32_e32 v185, v187
	v_pk_add_f32 v[148:149], v[148:149], v[184:185]
	v_lshlrev_b64 v[184:185], 6, v[176:177]
	v_lshl_add_u64 v[184:185], v[146:147], 0, v[184:185]
	v_pk_add_f32 v[148:149], v[148:149], v[148:149] op_sel:[0,1] op_sel_hi:[1,0]
	s_waitcnt vmcnt(0)
	v_mov_b32_e32 v184, v242
	v_mov_b32_e32 v185, v243
	v_mov_b32_e32 v186, v244
	v_mov_b32_e32 v187, v245
	v_mov_b32_e32 v192, v185
	v_mov_b32_e32 v193, v186
	v_mov_b32_e32 v185, v187
	v_mov_b32_e32 v149, v148
	v_pk_add_f32 v[184:185], v[192:193], v[184:185]
	s_nop 0
	v_permlane16_swap_b32_e32 v148, v149
	v_pk_add_f32 v[184:185], v[184:185], v[184:185] op_sel:[0,1] op_sel_hi:[1,0]
	v_add_f32_e32 v149, v148, v149
	v_mov_b32_e32 v148, v184
	s_nop 1
	v_permlane16_swap_b32_e32 v184, v148
	v_add_f32_e32 v148, v184, v148
	v_mov_b32_e32 v191, v149
	v_mov_b32_e32 v190, v148
	s_nop 0
	v_permlane32_swap_b32_e32 v149, v191
	v_permlane32_swap_b32_e32 v148, v190
	v_pk_add_f32 v[148:149], v[148:149], v[190:191]
	s_nop 0
	v_pk_fma_f32 v[148:149], v[148:149], s[18:19], v[174:175] op_sel_hi:[1,0,0]
	s_nop 0
	v_mul_f32_e32 v184, 0x4b800000, v149
	v_cmp_gt_f32_e64 s[6:7], s84, v149
	v_cmp_gt_f32_e32 vcc, s84, v148
	s_nop 0
	v_cndmask_b32_e64 v149, v149, v184, s[6:7]
	v_rsq_f32_e32 v149, v149
	s_nop 0
	v_mul_f32_e32 v184, 0x45800000, v149
	v_cndmask_b32_e64 v192, v149, v184, s[6:7]
	v_mul_f32_e32 v149, 0x4b800000, v148
	v_cndmask_b32_e32 v148, v148, v149, vcc
	v_rsq_f32_e32 v148, v148
	v_pk_fma_f32 v[96:97], v[96:97], v[192:193], v[140:141] op_sel_hi:[1,0,1]
	v_pk_fma_f32 v[94:95], v[94:95], v[192:193], v[138:139] op_sel_hi:[1,0,1]
	v_pk_fma_f32 v[84:85], v[84:85], v[192:193], v[136:137] op_sel_hi:[1,0,1]
	v_mul_f32_e32 v149, 0x45800000, v148
	v_cndmask_b32_e32 v190, v148, v149, vcc
	v_lshlrev_b64 v[148:149], 6, v[194:195]
	v_lshl_add_u64 v[148:149], v[146:147], 0, v[148:149]
	global_load_dwordx4 v[184:187], v[148:149], off
	global_load_dwordx4 v[242:245], v[148:149], off offset:1024
	global_load_dwordx4 v[246:249], v[148:149], off offset:2048
	v_pk_fma_f32 v[82:83], v[82:83], v[192:193], v[134:135] op_sel_hi:[1,0,1]
	v_pk_fma_f32 v[80:81], v[80:81], v[190:191], v[140:141] op_sel_hi:[1,0,1]
	v_pk_fma_f32 v[78:79], v[78:79], v[190:191], v[138:139] op_sel_hi:[1,0,1]
	v_pk_fma_f32 v[72:73], v[72:73], v[190:191], v[136:137] op_sel_hi:[1,0,1]
	v_pk_fma_f32 v[70:71], v[70:71], v[190:191], v[134:135] op_sel_hi:[1,0,1]
	s_waitcnt vmcnt(2)
	v_mov_b32_e32 v148, v185
	v_mov_b32_e32 v149, v186
	v_mov_b32_e32 v185, v187
	v_pk_add_f32 v[148:149], v[148:149], v[184:185]
	v_lshlrev_b64 v[184:185], 6, v[196:197]
	v_lshl_add_u64 v[184:185], v[146:147], 0, v[184:185]
	v_pk_add_f32 v[148:149], v[148:149], v[148:149] op_sel:[0,1] op_sel_hi:[1,0]
	s_waitcnt vmcnt(1)
	v_mov_b32_e32 v184, v242
	v_mov_b32_e32 v185, v243
	v_mov_b32_e32 v186, v244
	v_mov_b32_e32 v187, v245
	v_mov_b32_e32 v200, v185
	v_mov_b32_e32 v201, v186
	v_mov_b32_e32 v185, v187
	v_mov_b32_e32 v149, v148
	v_pk_add_f32 v[184:185], v[200:201], v[184:185]
	s_nop 0
	v_permlane16_swap_b32_e32 v148, v149
	v_pk_add_f32 v[184:185], v[184:185], v[184:185] op_sel:[0,1] op_sel_hi:[1,0]
	v_add_f32_e32 v149, v148, v149
	v_mov_b32_e32 v148, v184
	s_nop 1
	v_permlane16_swap_b32_e32 v184, v148
	v_add_f32_e32 v148, v184, v148
	v_mov_b32_e32 v199, v149
	v_mov_b32_e32 v198, v148
	s_nop 0
	v_permlane32_swap_b32_e32 v149, v199
	v_permlane32_swap_b32_e32 v148, v198
	v_pk_add_f32 v[148:149], v[148:149], v[198:199]
	s_nop 0
	v_pk_fma_f32 v[148:149], v[148:149], s[18:19], v[174:175] op_sel_hi:[1,0,0]
	s_nop 0
	v_mul_f32_e32 v184, 0x4b800000, v149
	v_cmp_gt_f32_e64 s[6:7], s84, v149
	v_cmp_gt_f32_e32 vcc, s84, v148
	s_nop 0
	v_cndmask_b32_e64 v149, v149, v184, s[6:7]
	v_rsq_f32_e32 v149, v149
	s_nop 0
	v_mul_f32_e32 v184, 0x45800000, v149
	v_cndmask_b32_e64 v200, v149, v184, s[6:7]
	v_mul_f32_e32 v149, 0x4b800000, v148
	v_cndmask_b32_e32 v148, v148, v149, vcc
	v_rsq_f32_e32 v148, v148
	v_pk_fma_f32 v[64:65], v[64:65], v[200:201], v[144:145] op_sel_hi:[1,0,1]
	v_pk_fma_f32 v[62:63], v[62:63], v[200:201], v[142:143] op_sel_hi:[1,0,1]
	v_pk_fma_f32 v[52:53], v[52:53], v[200:201], v[136:137] op_sel_hi:[1,0,1]
	v_mul_f32_e32 v149, 0x45800000, v148
	v_cndmask_b32_e32 v198, v148, v149, vcc
	v_lshlrev_b64 v[148:149], 6, v[202:203]
	v_lshl_add_u64 v[148:149], v[146:147], 0, v[148:149]
	v_pk_fma_f32 v[50:51], v[50:51], v[200:201], v[134:135] op_sel_hi:[1,0,1]
	v_pk_fma_f32 v[48:49], v[48:49], v[198:199], v[140:141] op_sel_hi:[1,0,1]
	v_pk_fma_f32 v[46:47], v[46:47], v[198:199], v[138:139] op_sel_hi:[1,0,1]
	v_pk_fma_f32 v[36:37], v[36:37], v[198:199], v[136:137] op_sel_hi:[1,0,1]
	v_pk_fma_f32 v[34:35], v[34:35], v[198:199], v[134:135] op_sel_hi:[1,0,1]
	s_waitcnt vmcnt(0)
	v_mov_b32_e32 v184, v246
	v_mov_b32_e32 v185, v247
	v_mov_b32_e32 v186, v248
	v_mov_b32_e32 v187, v249
	v_mov_b32_e32 v148, v185
	v_mov_b32_e32 v149, v186
	v_mov_b32_e32 v185, v187
	v_pk_add_f32 v[148:149], v[148:149], v[184:185]
	s_nop 0
	v_pk_add_f32 v[148:149], v[148:149], v[148:149] op_sel:[0,1] op_sel_hi:[1,0]
	s_nop 0
	v_mov_b32_e32 v149, v148
	s_nop 1
	v_permlane16_swap_b32_e32 v148, v149
	v_add_f32_e32 v207, v148, v149
	v_lshlrev_b64 v[148:149], 6, v[204:205]
	v_lshl_add_u64 v[146:147], v[146:147], 0, v[148:149]
	global_load_dwordx4 v[146:149], v[146:147], off
	v_mov_b32_e32 v209, v207
	s_nop 1
	v_permlane32_swap_b32_e32 v207, v209
	s_waitcnt vmcnt(0)
	v_mov_b32_e32 v184, v147
	v_mov_b32_e32 v185, v148
	v_mov_b32_e32 v147, v149
	v_pk_add_f32 v[146:147], v[184:185], v[146:147]
	s_nop 0
	v_pk_add_f32 v[146:147], v[146:147], v[146:147] op_sel:[0,1] op_sel_hi:[1,0]
	s_nop 0
	v_mov_b32_e32 v147, v146
	s_nop 1
	v_permlane16_swap_b32_e32 v146, v147
	v_add_f32_e32 v206, v146, v147
	v_mov_b32_e32 v208, v206
	s_nop 1
	v_permlane32_swap_b32_e32 v206, v208
	v_pk_add_f32 v[146:147], v[206:207], v[208:209]
	s_nop 0
	v_pk_fma_f32 v[146:147], v[146:147], s[18:19], v[174:175] op_sel_hi:[1,0,0]
	v_pk_fma_f32 v[174:175], v[124:125], v[170:171], v[140:141] op_sel_hi:[1,0,1]
	v_pk_fma_f32 v[124:125], v[122:123], v[170:171], v[138:139] op_sel_hi:[1,0,1]
	v_cvt_pk_bf16_f32 v122, v126, v127
	v_cvt_pk_bf16_f32 v123, v128, v129
	v_cvt_pk_bf16_f32 v124, v124, v125
	v_cvt_pk_bf16_f32 v125, v174, v175
	global_store_dwordx4 v[164:165], v[122:125], off
	v_mul_f32_e32 v148, 0x4b800000, v147
	v_cmp_gt_f32_e64 s[6:7], s84, v147
	v_pk_fma_f32 v[122:123], v[108:109], v[170:171], v[132:133] op_sel_hi:[1,0,1]
	v_pk_fma_f32 v[108:109], v[106:107], v[170:171], v[130:131] op_sel_hi:[1,0,1]
	v_cvt_pk_bf16_f32 v106, v114, v115
	v_cvt_pk_bf16_f32 v107, v116, v117
	v_cvt_pk_bf16_f32 v108, v108, v109
	v_cvt_pk_bf16_f32 v109, v122, v123
	global_store_dwordx4 v[164:165], v[106:109], off offset:256
	v_cndmask_b32_e64 v147, v147, v148, s[6:7]
	v_rsq_f32_e32 v147, v147
	v_lshlrev_b64 v[106:107], 12, v[166:167]
	v_lshl_add_u64 v[106:107], s[10:11], 0, v[106:107]
	v_lshl_add_u64 v[114:115], v[106:107], 0, v[162:163]
	v_pk_fma_f32 v[108:109], v[120:121], v[168:169], v[144:145] op_sel_hi:[1,0,1]
	v_pk_fma_f32 v[106:107], v[118:119], v[168:169], v[142:143] op_sel_hi:[1,0,1]
	v_mul_f32_e32 v148, 0x45800000, v147
	v_cvt_pk_bf16_f32 v106, v106, v107
	v_cvt_pk_bf16_f32 v107, v108, v109
	v_cvt_pk_bf16_f32 v108, v110, v111
	v_cvt_pk_bf16_f32 v109, v112, v113
	global_store_dwordx4 v[114:115], v[106:109], off
	v_cmp_gt_f32_e32 vcc, s84, v146
	v_cndmask_b32_e64 v148, v147, v148, s[6:7]
	v_pk_fma_f32 v[106:107], v[92:93], v[168:169], v[132:133] op_sel_hi:[1,0,1]
	v_pk_fma_f32 v[92:93], v[90:91], v[168:169], v[130:131] op_sel_hi:[1,0,1]
	v_cvt_pk_bf16_f32 v90, v98, v99
	v_cvt_pk_bf16_f32 v91, v100, v101
	v_cvt_pk_bf16_f32 v92, v92, v93
	v_cvt_pk_bf16_f32 v93, v106, v107
	global_store_dwordx4 v[114:115], v[90:93], off offset:256
	v_mul_f32_e32 v147, 0x4b800000, v146
	v_cndmask_b32_e32 v146, v146, v147, vcc
	v_lshlrev_b64 v[90:91], 12, v[172:173]
	v_lshl_add_u64 v[90:91], s[10:11], 0, v[90:91]
	v_lshl_add_u64 v[98:99], v[90:91], 0, v[162:163]
	v_pk_fma_f32 v[92:93], v[104:105], v[192:193], v[144:145] op_sel_hi:[1,0,1]
	v_pk_fma_f32 v[90:91], v[102:103], v[192:193], v[142:143] op_sel_hi:[1,0,1]
	v_rsq_f32_e32 v146, v146
	v_cvt_pk_bf16_f32 v90, v90, v91
	v_cvt_pk_bf16_f32 v91, v92, v93
	v_cvt_pk_bf16_f32 v92, v94, v95
	v_cvt_pk_bf16_f32 v93, v96, v97
	global_store_dwordx4 v[98:99], v[90:93], off
	v_pk_fma_f32 v[32:33], v[32:33], v[148:149], v[140:141] op_sel_hi:[1,0,1]
	v_pk_fma_f32 v[30:31], v[30:31], v[148:149], v[138:139] op_sel_hi:[1,0,1]
	v_pk_fma_f32 v[90:91], v[76:77], v[192:193], v[132:133] op_sel_hi:[1,0,1]
	v_pk_fma_f32 v[76:77], v[74:75], v[192:193], v[130:131] op_sel_hi:[1,0,1]
	v_cvt_pk_bf16_f32 v74, v82, v83
	v_cvt_pk_bf16_f32 v75, v84, v85
	v_cvt_pk_bf16_f32 v76, v76, v77
	v_cvt_pk_bf16_f32 v77, v90, v91
	global_store_dwordx4 v[98:99], v[74:77], off offset:256
	v_pk_fma_f32 v[20:21], v[20:21], v[148:149], v[136:137] op_sel_hi:[1,0,1]
	v_pk_fma_f32 v[18:19], v[18:19], v[148:149], v[134:135] op_sel_hi:[1,0,1]
	v_lshlrev_b64 v[74:75], 12, v[176:177]
	v_lshl_add_u64 v[74:75], s[10:11], 0, v[74:75]
	v_lshl_add_u64 v[82:83], v[74:75], 0, v[162:163]
	v_pk_fma_f32 v[76:77], v[88:89], v[190:191], v[144:145] op_sel_hi:[1,0,1]
	v_pk_fma_f32 v[74:75], v[86:87], v[190:191], v[142:143] op_sel_hi:[1,0,1]
	v_mul_f32_e32 v147, 0x45800000, v146
	v_cvt_pk_bf16_f32 v74, v74, v75
	v_cvt_pk_bf16_f32 v75, v76, v77
	v_cvt_pk_bf16_f32 v76, v78, v79
	v_cvt_pk_bf16_f32 v77, v80, v81
	global_store_dwordx4 v[82:83], v[74:77], off
	v_cndmask_b32_e32 v146, v146, v147, vcc
	v_pk_fma_f32 v[16:17], v[16:17], v[146:147], v[140:141] op_sel_hi:[1,0,1]
	v_pk_fma_f32 v[74:75], v[68:69], v[190:191], v[132:133] op_sel_hi:[1,0,1]
	v_pk_fma_f32 v[68:69], v[66:67], v[190:191], v[130:131] op_sel_hi:[1,0,1]
	v_cvt_pk_bf16_f32 v66, v70, v71
	v_cvt_pk_bf16_f32 v67, v72, v73
	v_cvt_pk_bf16_f32 v68, v68, v69
	v_cvt_pk_bf16_f32 v69, v74, v75
	global_store_dwordx4 v[82:83], v[66:69], off offset:256
	v_pk_fma_f32 v[14:15], v[14:15], v[146:147], v[138:139] op_sel_hi:[1,0,1]
	v_pk_fma_f32 v[8:9], v[8:9], v[146:147], v[136:137] op_sel_hi:[1,0,1]
	v_lshlrev_b64 v[66:67], 12, v[194:195]
	v_lshl_add_u64 v[66:67], s[10:11], 0, v[66:67]
	v_pk_fma_f32 v[68:69], v[60:61], v[200:201], v[140:141] op_sel_hi:[1,0,1]
	v_pk_fma_f32 v[60:61], v[58:59], v[200:201], v[138:139] op_sel_hi:[1,0,1]
	v_lshl_add_u64 v[66:67], v[66:67], 0, v[162:163]
	v_cvt_pk_bf16_f32 v58, v62, v63
	v_cvt_pk_bf16_f32 v59, v64, v65
	v_cvt_pk_bf16_f32 v60, v60, v61
	v_cvt_pk_bf16_f32 v61, v68, v69
	global_store_dwordx4 v[66:67], v[58:61], off
	v_pk_fma_f32 v[6:7], v[6:7], v[146:147], v[134:135] op_sel_hi:[1,0,1]
	s_mov_b64 s[6:7], -1
	v_pk_fma_f32 v[58:59], v[44:45], v[200:201], v[132:133] op_sel_hi:[1,0,1]
	v_pk_fma_f32 v[44:45], v[42:43], v[200:201], v[130:131] op_sel_hi:[1,0,1]
	v_cvt_pk_bf16_f32 v42, v50, v51
	v_cvt_pk_bf16_f32 v43, v52, v53
	v_cvt_pk_bf16_f32 v44, v44, v45
	v_cvt_pk_bf16_f32 v45, v58, v59
	global_store_dwordx4 v[66:67], v[42:45], off offset:256
	s_andn2_b64 vcc, exec, s[4:5]
	s_nop 0
	v_lshlrev_b64 v[42:43], 12, v[196:197]
	v_lshl_add_u64 v[42:43], s[10:11], 0, v[42:43]
	v_lshl_add_u64 v[50:51], v[42:43], 0, v[162:163]
	v_pk_fma_f32 v[44:45], v[56:57], v[198:199], v[144:145] op_sel_hi:[1,0,1]
	v_pk_fma_f32 v[42:43], v[54:55], v[198:199], v[142:143] op_sel_hi:[1,0,1]
	s_nop 0
	v_cvt_pk_bf16_f32 v42, v42, v43
	v_cvt_pk_bf16_f32 v43, v44, v45
	v_cvt_pk_bf16_f32 v44, v46, v47
	v_cvt_pk_bf16_f32 v45, v48, v49
	global_store_dwordx4 v[50:51], v[42:45], off
	s_nop 1
	v_pk_fma_f32 v[42:43], v[28:29], v[198:199], v[132:133] op_sel_hi:[1,0,1]
	v_pk_fma_f32 v[28:29], v[26:27], v[198:199], v[130:131] op_sel_hi:[1,0,1]
	v_cvt_pk_bf16_f32 v26, v34, v35
	v_cvt_pk_bf16_f32 v27, v36, v37
	v_cvt_pk_bf16_f32 v28, v28, v29
	v_cvt_pk_bf16_f32 v29, v42, v43
	global_store_dwordx4 v[50:51], v[26:29], off offset:256
	s_nop 1
	v_lshlrev_b64 v[26:27], 12, v[202:203]
	v_lshl_add_u64 v[26:27], s[10:11], 0, v[26:27]
	v_lshl_add_u64 v[34:35], v[26:27], 0, v[162:163]
	v_pk_fma_f32 v[28:29], v[40:41], v[148:149], v[144:145] op_sel_hi:[1,0,1]
	v_pk_fma_f32 v[26:27], v[38:39], v[148:149], v[142:143] op_sel_hi:[1,0,1]
	s_nop 0
	v_cvt_pk_bf16_f32 v26, v26, v27
	v_cvt_pk_bf16_f32 v27, v28, v29
	v_cvt_pk_bf16_f32 v28, v30, v31
	v_cvt_pk_bf16_f32 v29, v32, v33
	global_store_dwordx4 v[34:35], v[26:29], off
	s_nop 1
	v_pk_fma_f32 v[26:27], v[12:13], v[148:149], v[132:133] op_sel_hi:[1,0,1]
	v_pk_fma_f32 v[12:13], v[10:11], v[148:149], v[130:131] op_sel_hi:[1,0,1]
	v_cvt_pk_bf16_f32 v10, v18, v19
	v_cvt_pk_bf16_f32 v11, v20, v21
	v_cvt_pk_bf16_f32 v12, v12, v13
	v_cvt_pk_bf16_f32 v13, v26, v27
	global_store_dwordx4 v[34:35], v[10:13], off offset:256
	s_nop 1
	v_lshlrev_b64 v[10:11], 12, v[204:205]
	v_lshl_add_u64 v[10:11], s[10:11], 0, v[10:11]
	v_lshl_add_u64 v[18:19], v[10:11], 0, v[162:163]
	v_pk_fma_f32 v[12:13], v[24:25], v[146:147], v[144:145] op_sel_hi:[1,0,1]
	v_pk_fma_f32 v[10:11], v[22:23], v[146:147], v[142:143] op_sel_hi:[1,0,1]
	s_nop 0
	v_cvt_pk_bf16_f32 v10, v10, v11
	v_cvt_pk_bf16_f32 v11, v12, v13
	v_cvt_pk_bf16_f32 v12, v14, v15
	v_cvt_pk_bf16_f32 v13, v16, v17
	global_store_dwordx4 v[18:19], v[10:13], off
	s_nop 1
	v_pk_fma_f32 v[10:11], v[4:5], v[146:147], v[132:133] op_sel_hi:[1,0,1]
	v_pk_fma_f32 v[4:5], v[2:3], v[146:147], v[130:131] op_sel_hi:[1,0,1]
	v_cvt_pk_bf16_f32 v2, v6, v7
	v_cvt_pk_bf16_f32 v3, v8, v9
	v_cvt_pk_bf16_f32 v4, v4, v5
	v_cvt_pk_bf16_f32 v5, v10, v11
	global_store_dwordx4 v[18:19], v[2:5], off offset:256
	s_cbranch_vccnz .LBB0_175
	s_andn2_b64 vcc, exec, s[8:9]
	s_cbranch_vccnz .LBB0_174
	s_barrier
	s_branch .LBB0_174
